# GEMM tile headers: generic division by the tile-group size (always 8) replaced by a shift: removes a VALU rcp round trip and ~25 SALU per tile header
# baseline (speedup 1.0000x reference)
;     __host__ __device__ bool next(int i, Unit& u) const {
;         const long L = (long)i * G + c; if (L >= nwg) return false;
;         int wgid = (int)L; { const int q = nwg / NXCD, r = nwg % NXCD, xcd = wgid % NXCD, off = wgid / NXCD; wgid = (xcd < r ? xcd * (q + 1) : r * (q + 1) + (xcd - r) * q) + off; }
;         const int nig = WGM * nN, gid = wgid / nig, fm = gid * WGM, gsz = (nM - fm) < WGM ? (nM - fm) : WGM;
;         u.pm = fm + ((wgid % nig) % gsz); u.pn = (wgid % nig) / gsz; return true;
.LBB0_210:
	s_ashr_i32 s4, s6, 3
	s_add_i32 s4, s16, s4
	s_ashr_i32 s5, s4, 31
	s_lshr_b32 s5, s5, 25
	s_add_i32 s5, s4, s5
	s_ashr_i32 s6, s5, 7
	s_lshl_b32 s6, s6, 3
	s_sub_i32 s7, 64, s6
	s_min_i32 s7, s7, 8
	s_and_b32 s5, s5, 0xffffff80
	s_sub_i32 s4, s4, s5
	s_ashr_i32 s72, s4, 3
	s_mul_i32 s5, s72, s7
	s_sub_i32 s4, s4, s5
	s_add_i32 s88, s6, s4

;     __host__ __device__ bool next(int i, Unit& u) const {
;         const long L = (long)i * G + c; if (L >= nwg) return false;
;         int wgid = (int)L; { const int q = nwg / NXCD, r = nwg % NXCD, xcd = wgid % NXCD, off = wgid / NXCD; wgid = (xcd < r ? xcd * (q + 1) : r * (q + 1) + (xcd - r) * q) + off; }
;         const int nig = WGM * nN, gid = wgid / nig, fm = gid * WGM, gsz = (nM - fm) < WGM ? (nM - fm) : WGM;
;         u.pm = fm + ((wgid % nig) % gsz); u.pn = (wgid % nig) / gsz; return true;
.LBB0_230:
	s_ashr_i32 s10, s46, 3
	s_add_i32 s10, s52, s10
	s_ashr_i32 s11, s10, 31
	s_lshr_b32 s11, s11, 23
	s_add_i32 s11, s10, s11
	s_ashr_i32 s46, s11, 9
	s_lshl_b32 s46, s46, 3
	s_sub_i32 s47, 8, s46
	s_min_i32 s47, s47, 8
	s_and_b32 s11, s11, 0xfffffe00
	s_sub_i32 s11, s10, s11
	s_ashr_i32 s10, s11, 3
	s_mul_i32 s47, s10, s47
	s_sub_i32 s11, s11, s47
	s_add_i32 s46, s46, s11

;     __host__ __device__ bool next(int i, Unit& u) const {
;         const long L = (long)i * G + c; if (L >= nwg) return false;
;         int wgid = (int)L; { const int q = nwg / NXCD, r = nwg % NXCD, xcd = wgid % NXCD, off = wgid / NXCD; wgid = (xcd < r ? xcd * (q + 1) : r * (q + 1) + (xcd - r) * q) + off; }
;         const int nig = WGM * nN, gid = wgid / nig, fm = gid * WGM, gsz = (nM - fm) < WGM ? (nM - fm) : WGM;
;         u.pm = fm + ((wgid % nig) % gsz); u.pn = (wgid % nig) / gsz; return true;
.LBB0_424:
	s_ashr_i32 s42, s46, 3
	s_add_i32 s42, s52, s42
	s_ashr_i32 s43, s42, 31
	s_lshr_b32 s43, s43, 26
	s_add_i32 s43, s42, s43
	s_ashr_i32 s46, s43, 6
	s_lshl_b32 s46, s46, 3
	s_sub_i32 s47, 64, s46
	s_min_i32 s47, s47, 8
	s_andn2_b32 s43, s43, 63
	s_sub_i32 s43, s42, s43
	s_ashr_i32 s42, s43, 3
	s_mul_i32 s47, s42, s47
	s_sub_i32 s43, s43, s47
	s_add_i32 s46, s46, s43

;     __host__ __device__ bool next(int i, Unit& u) const {
;         const long L = (long)i * G + c; if (L >= nwg) return false;
;         int wgid = (int)L; { const int q = nwg / NXCD, r = nwg % NXCD, xcd = wgid % NXCD, off = wgid / NXCD; wgid = (xcd < r ? xcd * (q + 1) : r * (q + 1) + (xcd - r) * q) + off; }
;         const int nig = WGM * nN, gid = wgid / nig, fm = gid * WGM, gsz = (nM - fm) < WGM ? (nM - fm) : WGM;
;         u.pm = fm + ((wgid % nig) % gsz); u.pn = (wgid % nig) / gsz; return true;
.LBB0_603:
	s_ashr_i32 s6, s17, 3
	s_add_i32 s6, s44, s6
	s_ashr_i32 s7, s6, 31
	s_lshr_b32 s7, s7, 24
	s_add_i32 s7, s6, s7
	s_ashr_i32 s16, s7, 8
	s_lshl_b32 s16, s16, 3
	s_sub_i32 s17, 64, s16
	s_min_i32 s17, s17, 8
	s_and_b32 s7, s7, 0xffffff00
	s_sub_i32 s7, s6, s7
	s_ashr_i32 s6, s7, 3
	s_mul_i32 s17, s6, s17
	s_sub_i32 s7, s7, s17
	s_add_i32 s94, s16, s7
	s_and_b32 s16, s94, 7
	s_and_b32 s17, s94, -8
	s_lshr_b32 s7, s6, 4
	s_xor_b32 s7, s7, 1
	s_lshl_b32 s7, s7, 2
	s_add_i32 s17, s17, s7
	s_and_b32 s7, s16, 3
	s_add_i32 s94, s17, s7
	s_lshr_b32 s7, s6, 2
	s_and_b32 s7, s7, 3
	s_lshl_b32 s7, s7, 3
	s_and_b32 s17, s6, 3
	s_lshl_b32 s17, s17, 1
	s_add_i32 s7, s7, s17
	s_lshr_b32 s16, s16, 2
	s_add_i32 s6, s7, s16

;     __host__ __device__ bool next(int i, Unit& u) const {
;         const long L = (long)i * G + c; if (L >= nwg) return false;
;         int wgid = (int)L; { const int q = nwg / NXCD, r = nwg % NXCD, xcd = wgid % NXCD, off = wgid / NXCD; wgid = (xcd < r ? xcd * (q + 1) : r * (q + 1) + (xcd - r) * q) + off; }
;         const int nig = WGM * nN, gid = wgid / nig, fm = gid * WGM, gsz = (nM - fm) < WGM ? (nM - fm) : WGM;
;         u.pm = fm + ((wgid % nig) % gsz); u.pn = (wgid % nig) / gsz; return true;
.LBB0_700:
	s_ashr_i32 s38, s46, 3
	s_add_i32 s38, s52, s38
	s_ashr_i32 s39, s38, 31
	s_lshr_b32 s39, s39, 26
	s_add_i32 s39, s38, s39
	s_ashr_i32 s42, s39, 6
	s_lshl_b32 s43, s42, 3
	s_sub_i32 s42, 64, s43
	s_min_i32 s46, s42, 8
	s_andn2_b32 s39, s39, 63
	s_sub_i32 s38, s38, s39
	s_ashr_i32 s42, s38, 3
	s_mul_i32 s39, s42, s46
	s_sub_i32 s38, s38, s39
	s_add_i32 s46, s43, s38
	s_and_b32 s38, s46, 7
	s_and_b32 s39, s46, -8
	s_lshr_b32 s43, s42, 2
	s_lshl_b32 s43, s43, 2
	s_add_i32 s39, s39, s43
	s_and_b32 s43, s38, 3
	s_add_i32 s46, s39, s43
	s_and_b32 s43, s42, 3
	s_lshl_b32 s43, s43, 1
	s_lshr_b32 s38, s38, 2
	s_add_i32 s42, s43, s38
